# all of the W_down f32->bf16 conversion moved from the attention phase to the idle 64 CUs of the last gate/up GEMM round (item range constants only)
# baseline (speedup 1.0000x reference)
; #define LAS __attribute__((address_space(3)))
; template <bool NT> __device__ __forceinline__ void p0_weights(Frame& F, int lo, int NITEMS, int widx, int nworkers) {
;     LAS float* scr = (LAS float*)(F.lds + RING_OFF + F.wave * 16640);
;     const int gw = widx * NWAVES + F.wave, NGW = nworkers * NWAVES;
;     const int g4 = (F.lane & 15) * 4;
;     f32x4 va[16], vb[16];
;     int it = lo + gw; if (it >= NITEMS) return;
;     TrItem ta = p0_item(F, it, g4), tb = ta;
;     tr_load<NT>(va, ta, F.lane);
.LBB0_1208:
	s_add_u32 s90, s82, 0x20c00000
	s_addc_u32 s91, s83, 0
	s_cmp_lt_i32 s86, 7
	s_cselect_b64 s[0:1], -1, 0
	s_cmp_gt_i32 s87, 6
	s_cselect_b64 s[4:5], -1, 0
	s_and_b64 s[0:1], s[0:1], s[4:5]
	s_andn2_b64 vcc, exec, s[0:1]
	s_cbranch_vccnz .LBB0_1681
	v_mov_b32_e32 v135, v0
	s_nop 0
	v_readfirstlane_b32 s0, v135
	s_ashr_i32 s18, s0, 6
	s_cmp_gt_u32 s95, 31
	v_and_b32_e32 v1, 63, v135
	s_cbranch_scc0 .LBB0_1218
	s_cmpk_lt_i32 s3, 0x78
	s_cbranch_scc1 .LBB0_1219
	s_add_i32 s0, s95, 0xffffffa0
	s_cmp_gt_u32 s0, 23
	s_cbranch_scc0 .LBB0_1220
	s_cmpk_gt_i32 s95, 0x5f
	v_mov_b32_e32 v2, v135
	s_cbranch_scc1 .LBB0_1419
	s_lshl_b32 s0, s95, 3
	s_add_i32 s0, s0, s18
	s_add_i32 s27, s0, 0x3740
	s_cmp_gt_i32 s27, 0x9e3f
	s_cbranch_scc1 .LBB0_1418
	s_add_u32 s2, s82, 0x2000000
	s_addc_u32 s16, s83, 0
	s_add_u32 s17, s82, 0x9800000
	s_addc_u32 s19, s83, 0
	s_add_u32 s20, s82, 0xbc00000
	s_addc_u32 s21, s83, 0
	s_add_u32 s0, s82, 0x17000000
	v_lshlrev_b32_e32 v2, 2, v1
	s_addc_u32 s1, s83, 0
	s_cmpk_gt_i32 s27, 0x383f
	v_and_b32_e32 v134, 60, v2
	s_cbranch_scc0 .LBB0_1222
	s_cmpk_gt_u32 s27, 0x483f
	s_cbranch_scc0 .LBB0_1223
	s_cmpk_gt_u32 s27, 0x9e3f
	s_cbranch_scc0 .LBB0_1224
	s_add_i32 s4, s27, 0x61c0
	s_and_b32 s5, s4, 0xffff
	s_mul_i32 s5, s5, 0xbe83
	s_lshr_b32 s6, s5, 23
	s_mul_i32 s5, s6, 0xac
	s_sub_i32 s4, s4, s5
	s_lshl_b32 s4, s4, 6
	s_and_b32 s7, s4, 0xffc0
	s_lshl_b32 s4, s7, 14
	s_add_u32 s4, s78, s4
	s_addc_u32 s5, s79, 0
	s_lshl_b32 s8, s6, 8
	s_add_u32 s4, s4, s8
	s_addc_u32 s5, s5, 0
	v_lshlrev_b32_e32 v2, 2, v134
	s_waitcnt lgkmcnt(0)
	v_mov_b32_e32 v3, 0
	s_mul_i32 s6, s6, 0x158000
	v_lshl_add_u64 v[2:3], s[4:5], 0, v[2:3]
	s_add_u32 s4, s0, s6
	s_addc_u32 s5, s1, 0
	s_lshl_b32 s6, s7, 1
	s_add_u32 s6, s4, s6
	s_addc_u32 s7, s5, 0
	s_mov_b64 s[4:5], 0
	s_branch .LBB0_1225

; __device__ __forceinline__ TrItem p0_item(Frame& F, int it, int g4) {
;     constexpr int I_IN = (DM / 64) * (NPT / 64), I_OUT = (DM / 64) * (DM / 64), I_GU = (DM / 64) * (2 * FF / 64);
;     bf16* win_t = (bf16*)(F.ws + WS_WIN); bf16* wout_t = (bf16*)(F.ws + WS_WOUT); bf16* wgu_t = (bf16*)(F.ws + WS_WGU); bf16* wd_t = (bf16*)(F.ws + WS_WD);
;     TrItem t; int r = it;
;     if (r < I_IN) { const int kb = r % (DM / 64), nb = r / (DM / 64); const int sc = win_srccol(nb * 64 + g4);
;         t.colp = sc >= 0 ? F.w_in + (size_t)(kb * 64) * IN_COLS + sc : nullptr; t.ldw = IN_COLS; t.K = LDWIN; t.dst = win_t + (size_t)(nb * 64) * LDWIN + kb * 64; return t; } r -= I_IN;
;     if (r < I_OUT) { const int kb = r % (DM / 64), nb = r / (DM / 64);
;         t.colp = F.w_out + (size_t)(kb * 64) * DM + nb * 64 + g4; t.ldw = DM; t.K = LDWOUT; t.dst = wout_t + (size_t)(nb * 64) * LDWOUT + kb * 64; return t; } r -= I_OUT;
;     if (r < I_GU) { const int kb = r % (DM / 64), nb = r / (DM / 64); const int n = nb * 64 + g4;
;         const float* src = ((n >> 7) & 1) ? F.w_up : F.w_gate;
;         t.colp = src + (size_t)(kb * 64) * FF + (n >> 8) * 128 + (n & 127); t.ldw = FF; t.K = LDWGU; t.dst = wgu_t + (size_t)(nb * 64) * LDWGU + kb * 64; return t; } r -= I_GU;
;     { const int kb = r % (FF / 64), nb = r / (FF / 64);
;         t.colp = F.w_down + (size_t)(kb * 64) * DM + nb * 64 + g4; t.ldw = DM; t.K = FF; t.dst = wd_t + (size_t)(nb * 64) * FF + kb * 64; return t; }
; template <bool NT> __device__ __forceinline__ void p0_weights(Frame& F, int lo, int NITEMS, int widx, int nworkers) {
;     ...
;     for (;;) {
;         const bool hb = it + NGW < NITEMS;
;         if (hb) { tb = p0_item(F, it + NGW, g4); tr_load<NT>(vb, tb, F.lane); }
.LBB0_1290:
	s_cmp_lt_i32 s27, 0x9c40
	s_cselect_b64 s[6:7], -1, 0
	s_cmp_gt_i32 s27, 0x9c3f
	s_cbranch_scc1 .LBB0_1350
	s_add_i32 s29, s27, 0x200
	s_cmpk_gt_i32 s27, 0x363f
	s_cbranch_scc0 .LBB0_1296
	s_cmpk_gt_u32 s29, 0x483f
	s_cbranch_scc0 .LBB0_1297
	s_cmpk_gt_u32 s29, 0x9e3f
	s_cbranch_scc0 .LBB0_1358
	s_add_i32 s4, s29, 0x61c0
	s_and_b32 s8, s4, 0xffff
	s_mul_i32 s8, s8, 0xbe83
	s_lshr_b32 s8, s8, 23
	s_mul_i32 s9, s8, 0xac
	s_sub_i32 s4, s4, s9
	s_lshl_b32 s4, s4, 6
	s_and_b32 s4, s4, 0xffc0
	s_lshl_b32 s9, s4, 14
	s_add_u32 s9, s78, s9
	s_addc_u32 s10, s79, 0
	s_lshl_b32 s11, s8, 6
	s_lshl_b32 s8, s8, 8
	s_add_u32 s8, s9, s8
	s_addc_u32 s9, s10, 0
	v_lshlrev_b32_e32 v4, 2, v134
	v_mov_b32_e32 v5, v2
	v_mov_b64_e32 v[54:55], s[0:1]
	v_lshl_add_u64 v[4:5], s[8:9], 0, v[4:5]
	v_mad_u64_u32 v[54:55], s[8:9], s11, v170, v[54:55]
	s_lshl_b32 s4, s4, 1
	v_lshl_add_u64 v[156:157], v[54:55], 0, s[4:5]
	s_cbranch_execz .LBB0_1359
	s_mov_b64 s[8:9], 0x1000
	s_movk_i32 s28, 0x2b00
	s_cbranch_execz .LBB0_1298
	s_branch .LBB0_1299

; #define GAS __attribute__((address_space(1)))
; #define LAS __attribute__((address_space(3)))
; #define LDS_WAIT() asm volatile("s_waitcnt lgkmcnt(0)" ::: "memory")
; __device__ __forceinline__ unsigned pk2(float lo, float hi) { pkf32x2 v = {lo, hi}; pkbf16x2 b = __builtin_convertvector(v, pkbf16x2); return __builtin_bit_cast(unsigned, b); }
; template <bool NT> __device__ __forceinline__ void tr_store(const f32x4 (&v)[16], const TrItem& it, LAS float* scr, int lane) {
;     const int kq = lane >> 4, g = lane & 15;
; #pragma unroll
;     for (int i = 0; i < 16; ++i) { LAS float* d = scr + (4 * i + kq) * 65 + 4 * g; d[0] = v[i].x; d[1] = v[i].y; d[2] = v[i].z; d[3] = v[i].w; }
;     LDS_WAIT(); asm volatile("" ::: "memory");
;     const int c = lane >> 3, rr = lane & 7;
; #pragma unroll
;     for (int j = 0; j < 8; ++j) { const int n = 8 * j + rr; const LAS float* s = scr + (8 * c) * 65 + n;
;         v4u o; o.x = pk2(s[0 * 65], s[1 * 65]); o.y = pk2(s[2 * 65], s[3 * 65]); o.z = pk2(s[4 * 65], s[5 * 65]); o.w = pk2(s[6 * 65], s[7 * 65]);
;         GAS v4u* q = (GAS v4u*)(it.dst + (size_t)n * it.K + 8 * c); if (NT) __builtin_nontemporal_store(o, q); else *q = o; }
;     LDS_WAIT(); asm volatile("" ::: "memory");
; }
.LBB0_1350:
	v_add_u32_e32 v174, 0x410, v172
	v_add_u32_e32 v175, 0x418, v172
	v_add_u32_e32 v176, 0x820, v172
	v_add_u32_e32 v177, 0x828, v172
	v_add_u32_e32 v178, 0xc30, v172
	v_add_u32_e32 v179, 0xc38, v172
	v_add_u32_e32 v180, 0x1040, v172
	v_add_u32_e32 v181, 0x1048, v172
	v_add_u32_e32 v182, 0x1450, v172
	v_add_u32_e32 v183, 0x1458, v172
	v_add_u32_e32 v184, 0x1860, v172
	v_add_u32_e32 v185, 0x1868, v172
	v_add_u32_e32 v186, 0x1c70, v172
	v_add_u32_e32 v187, 0x1c78, v172
	v_add_u32_e32 v188, 0x2080, v172
	v_add_u32_e32 v189, 0x2088, v172
	v_add_u32_e32 v190, 0x2490, v172
	v_add_u32_e32 v191, 0x2498, v172
	v_add_u32_e32 v192, 0x28a0, v172
	v_add_u32_e32 v193, 0x28a8, v172
	v_add_u32_e32 v194, 0x2cb0, v172
	v_add_u32_e32 v195, 0x2cb8, v172
	v_add_u32_e32 v196, 0x30c0, v172
	v_add_u32_e32 v197, 0x30c8, v172
	v_add_u32_e32 v198, 0x34d0, v172
	v_add_u32_e32 v199, 0x34d8, v172
	v_add_u32_e32 v200, 0x38e0, v172
	v_add_u32_e32 v201, 0x38e8, v172
	v_add_u32_e32 v202, 0x3cf0, v172
	v_add_u32_e32 v203, 0x3cf8, v172
	s_waitcnt vmcnt(0)
	ds_write2_b32 v172, v10, v11 offset1:1
	ds_write2_b32 v172, v12, v13 offset0:2 offset1:3
	ds_write2_b32 v174, v6, v7 offset1:1
	ds_write2_b32 v175, v8, v9 offset1:1
	ds_write2_b32 v176, v14, v15 offset1:1
	ds_write2_b32 v177, v16, v17 offset1:1
	ds_write2_b32 v178, v18, v19 offset1:1
	ds_write2_b32 v179, v20, v21 offset1:1
	ds_write2_b32 v180, v22, v23 offset1:1
	ds_write2_b32 v181, v24, v25 offset1:1
	ds_write2_b32 v182, v26, v27 offset1:1
	ds_write2_b32 v183, v28, v29 offset1:1
	ds_write2_b32 v184, v30, v31 offset1:1
	ds_write2_b32 v185, v32, v33 offset1:1
	ds_write2_b32 v186, v34, v35 offset1:1
	ds_write2_b32 v187, v36, v37 offset1:1
	ds_write2_b32 v188, v38, v39 offset1:1
	ds_write2_b32 v189, v40, v41 offset1:1
	ds_write2_b32 v190, v42, v43 offset1:1
	ds_write2_b32 v191, v44, v45 offset1:1
	ds_write2_b32 v192, v46, v47 offset1:1
	ds_write2_b32 v193, v48, v49 offset1:1
	ds_write2_b32 v194, v50, v51 offset1:1
	ds_write2_b32 v195, v52, v53 offset1:1
	ds_write2_b32 v196, v62, v63 offset1:1
	ds_write2_b32 v197, v64, v65 offset1:1
	ds_write2_b32 v198, v74, v75 offset1:1
	ds_write2_b32 v199, v76, v77 offset1:1
	ds_write2_b32 v200, v86, v87 offset1:1
	ds_write2_b32 v201, v88, v89 offset1:1
	ds_write2_b32 v202, v90, v91 offset1:1
	ds_write2_b32 v203, v92, v93 offset1:1
	s_waitcnt lgkmcnt(0)
	v_add_u32_e32 v173, 0x400, v169
	ds_read2_b32 v[4:5], v169 offset0:65 offset1:73
	ds_read2_b32 v[160:161], v169 offset1:8
	ds_read2_b32 v[208:209], v169 offset0:130 offset1:138
	ds_read2_b32 v[210:211], v169 offset0:195 offset1:203
	ds_read2_b32 v[212:213], v173 offset0:4 offset1:12
	ds_read2_b32 v[214:215], v173 offset0:69 offset1:77
	ds_read2_b32 v[216:217], v173 offset0:134 offset1:142
	ds_read2_b32 v[218:219], v173 offset0:199 offset1:207
	v_lshlrev_b32_e32 v158, 1, v138
	v_mov_b32_e32 v159, v2
	v_lshl_add_u64 v[220:221], v[154:155], 0, v[158:159]
	v_mad_u64_u32 v[222:223], s[8:9], s22, v136, 0
	s_waitcnt lgkmcnt(6)
	v_cvt_pk_bf16_f32 v204, v160, v4
	s_waitcnt lgkmcnt(4)
	v_cvt_pk_bf16_f32 v205, v208, v210
	s_waitcnt lgkmcnt(2)
	v_cvt_pk_bf16_f32 v206, v212, v214
	s_waitcnt lgkmcnt(0)
	v_cvt_pk_bf16_f32 v207, v216, v218
	v_lshl_add_u64 v[222:223], v[222:223], 1, v[220:221]
	global_store_dwordx4 v[222:223], v[204:207], off nt
	s_andn2_b64 vcc, exec, s[6:7]
	s_mov_b64 s[6:7], 0
	v_cvt_pk_bf16_f32 v204, v161, v5
	v_cvt_pk_bf16_f32 v205, v209, v211
	v_cvt_pk_bf16_f32 v206, v213, v215
	v_cvt_pk_bf16_f32 v207, v217, v219
	ds_read2_b32 v[160:161], v169 offset0:16 offset1:24
	ds_read2_b32 v[208:209], v169 offset0:81 offset1:89
	ds_read2_b32 v[210:211], v169 offset0:146 offset1:154
	ds_read2_b32 v[212:213], v169 offset0:211 offset1:219
	ds_read2_b32 v[214:215], v173 offset0:20 offset1:28
	ds_read2_b32 v[216:217], v173 offset0:85 offset1:93
	ds_read2_b32 v[218:219], v173 offset0:150 offset1:158
	ds_read2_b32 v[222:223], v173 offset0:215 offset1:223
	v_mad_u64_u32 v[4:5], s[8:9], s22, v140, 0
	v_lshl_add_u64 v[4:5], v[4:5], 1, v[220:221]
	global_store_dwordx4 v[4:5], v[204:207], off nt
	v_mad_u64_u32 v[4:5], s[8:9], s22, v142, 0
	s_waitcnt lgkmcnt(6)
	v_cvt_pk_bf16_f32 v204, v160, v208
	s_waitcnt lgkmcnt(4)
	v_cvt_pk_bf16_f32 v205, v210, v212
	s_waitcnt lgkmcnt(2)
	v_cvt_pk_bf16_f32 v206, v214, v216
	s_waitcnt lgkmcnt(0)
	v_cvt_pk_bf16_f32 v207, v218, v222
	v_lshl_add_u64 v[4:5], v[4:5], 1, v[220:221]
	global_store_dwordx4 v[4:5], v[204:207], off nt
	v_mad_u64_u32 v[4:5], s[8:9], s22, v144, 0
	s_nop 0
	v_cvt_pk_bf16_f32 v204, v161, v209
	v_cvt_pk_bf16_f32 v205, v211, v213
	v_cvt_pk_bf16_f32 v206, v215, v217
	v_cvt_pk_bf16_f32 v207, v219, v223
	ds_read2_b32 v[160:161], v169 offset0:32 offset1:40
	ds_read2_b32 v[208:209], v169 offset0:97 offset1:105
	ds_read2_b32 v[210:211], v169 offset0:162 offset1:170
	ds_read2_b32 v[212:213], v169 offset0:227 offset1:235
	ds_read2_b32 v[214:215], v173 offset0:36 offset1:44
	ds_read2_b32 v[216:217], v173 offset0:101 offset1:109
	ds_read2_b32 v[218:219], v173 offset0:166 offset1:174
	ds_read2_b32 v[222:223], v173 offset0:231 offset1:239
	v_lshl_add_u64 v[4:5], v[4:5], 1, v[220:221]
	global_store_dwordx4 v[4:5], v[204:207], off nt
	v_mad_u64_u32 v[4:5], s[8:9], s22, v146, 0
	s_waitcnt lgkmcnt(6)
	v_cvt_pk_bf16_f32 v204, v160, v208
	s_waitcnt lgkmcnt(4)
	v_cvt_pk_bf16_f32 v205, v210, v212
	s_waitcnt lgkmcnt(2)
	v_cvt_pk_bf16_f32 v206, v214, v216
	s_waitcnt lgkmcnt(0)
	v_cvt_pk_bf16_f32 v207, v218, v222
	v_lshl_add_u64 v[4:5], v[4:5], 1, v[220:221]
	global_store_dwordx4 v[4:5], v[204:207], off nt
	v_mad_u64_u32 v[4:5], s[8:9], s22, v148, 0
	s_nop 0
	v_cvt_pk_bf16_f32 v204, v161, v209
	v_cvt_pk_bf16_f32 v205, v211, v213
	v_cvt_pk_bf16_f32 v206, v215, v217
	v_cvt_pk_bf16_f32 v207, v219, v223
	ds_read2_b32 v[160:161], v169 offset0:48 offset1:56
	ds_read2_b32 v[208:209], v169 offset0:113 offset1:121
	ds_read2_b32 v[210:211], v169 offset0:178 offset1:186
	ds_read2_b32 v[212:213], v169 offset0:243 offset1:251
	ds_read2_b32 v[214:215], v173 offset0:52 offset1:60
	ds_read2_b32 v[216:217], v173 offset0:117 offset1:125
	ds_read2_b32 v[218:219], v173 offset0:182 offset1:190
	ds_read2_b32 v[222:223], v173 offset0:247 offset1:255
	v_lshl_add_u64 v[4:5], v[4:5], 1, v[220:221]
	global_store_dwordx4 v[4:5], v[204:207], off nt
	v_mad_u64_u32 v[4:5], s[8:9], s22, v150, 0
	s_waitcnt lgkmcnt(6)
	v_cvt_pk_bf16_f32 v204, v160, v208
	s_waitcnt lgkmcnt(4)
	v_cvt_pk_bf16_f32 v205, v210, v212
	s_waitcnt lgkmcnt(2)
	v_cvt_pk_bf16_f32 v206, v214, v216
	s_waitcnt lgkmcnt(0)
	v_cvt_pk_bf16_f32 v207, v218, v222
	v_lshl_add_u64 v[4:5], v[4:5], 1, v[220:221]
	global_store_dwordx4 v[4:5], v[204:207], off nt
	v_mad_u64_u32 v[4:5], s[8:9], s22, v152, 0
	s_nop 0
	v_cvt_pk_bf16_f32 v204, v161, v209
	v_cvt_pk_bf16_f32 v205, v211, v213
	v_cvt_pk_bf16_f32 v206, v215, v217
	v_cvt_pk_bf16_f32 v207, v219, v223
	v_lshl_add_u64 v[4:5], v[4:5], 1, v[220:221]
	global_store_dwordx4 v[4:5], v[204:207], off nt
	s_waitcnt lgkmcnt(0)
	s_cbranch_vccnz .LBB0_1289
; __device__ __forceinline__ TrItem p0_item(Frame& F, int it, int g4) {
;     constexpr int I_IN = (DM / 64) * (NPT / 64), I_OUT = (DM / 64) * (DM / 64), I_GU = (DM / 64) * (2 * FF / 64);
;     bf16* win_t = (bf16*)(F.ws + WS_WIN); bf16* wout_t = (bf16*)(F.ws + WS_WOUT); bf16* wgu_t = (bf16*)(F.ws + WS_WGU); bf16* wd_t = (bf16*)(F.ws + WS_WD);
;     TrItem t; int r = it;
;     if (r < I_IN) { const int kb = r % (DM / 64), nb = r / (DM / 64); const int sc = win_srccol(nb * 64 + g4);
;         t.colp = sc >= 0 ? F.w_in + (size_t)(kb * 64) * IN_COLS + sc : nullptr; t.ldw = IN_COLS; t.K = LDWIN; t.dst = win_t + (size_t)(nb * 64) * LDWIN + kb * 64; return t; } r -= I_IN;
;     if (r < I_OUT) { const int kb = r % (DM / 64), nb = r / (DM / 64);
;         t.colp = F.w_out + (size_t)(kb * 64) * DM + nb * 64 + g4; t.ldw = DM; t.K = LDWOUT; t.dst = wout_t + (size_t)(nb * 64) * LDWOUT + kb * 64; return t; } r -= I_OUT;
;     if (r < I_GU) { const int kb = r % (DM / 64), nb = r / (DM / 64); const int n = nb * 64 + g4;
;         const float* src = ((n >> 7) & 1) ? F.w_up : F.w_gate;
;         t.colp = src + (size_t)(kb * 64) * FF + (n >> 8) * 128 + (n & 127); t.ldw = FF; t.K = LDWGU; t.dst = wgu_t + (size_t)(nb * 64) * LDWGU + kb * 64; return t; } r -= I_GU;
;     { const int kb = r % (FF / 64), nb = r / (FF / 64);
;         t.colp = F.w_down + (size_t)(kb * 64) * DM + nb * 64 + g4; t.ldw = DM; t.K = FF; t.dst = wd_t + (size_t)(nb * 64) * FF + kb * 64; return t; }
; template <bool NT> __device__ __forceinline__ void p0_weights(Frame& F, int lo, int NITEMS, int widx, int nworkers) {
;     ...
;         const bool ha = it + 2 * NGW < NITEMS;
;         if (ha) { ta = p0_item(F, it + 2 * NGW, g4); tr_load<NT>(va, ta, F.lane); }
	s_cmp_lt_i32 s27, 0x9a40
	s_cselect_b64 s[6:7], -1, 0
	s_cmp_gt_i32 s27, 0x9a3f
	s_cbranch_scc1 .LBB0_1356
	s_add_i32 s29, s27, 0x400
	s_cmpk_gt_i32 s27, 0x343f
	s_cbranch_scc0 .LBB0_1357
	s_cmpk_gt_u32 s29, 0x483f
	s_cbranch_scc0 .LBB0_1360
	s_cmpk_gt_u32 s29, 0x9e3f
	s_cbranch_scc0 .LBB0_1361
	s_add_i32 s4, s29, 0x61c0
	s_and_b32 s8, s4, 0xffff
	s_mul_i32 s8, s8, 0xbe83
	s_lshr_b32 s8, s8, 23
	s_mul_i32 s9, s8, 0xac
	s_sub_i32 s4, s4, s9
	s_lshl_b32 s4, s4, 6
	s_and_b32 s4, s4, 0xffc0
	s_lshl_b32 s9, s4, 14
	s_add_u32 s9, s78, s9
	s_addc_u32 s10, s79, 0
	s_lshl_b32 s11, s8, 6
	s_lshl_b32 s8, s8, 8
	s_add_u32 s8, s9, s8
	s_addc_u32 s9, s10, 0
	v_lshlrev_b32_e32 v4, 2, v134
	v_mov_b32_e32 v5, v2
	v_lshl_add_u64 v[160:161], s[8:9], 0, v[4:5]
	v_mov_b64_e32 v[4:5], s[0:1]
	v_mad_u64_u32 v[4:5], s[8:9], s11, v170, v[4:5]
	s_lshl_b32 s4, s4, 1
	v_lshl_add_u64 v[154:155], v[4:5], 0, s[4:5]
	s_mov_b64 s[8:9], 0
	s_branch .LBB0_1362

; #define LAS __attribute__((address_space(3)))
; template <bool NT> __device__ __forceinline__ void p0_weights(Frame& F, int lo, int NITEMS, int widx, int nworkers) {
;     LAS float* scr = (LAS float*)(F.lds + RING_OFF + F.wave * 16640);
;     const int gw = widx * NWAVES + F.wave, NGW = nworkers * NWAVES;
;     const int g4 = (F.lane & 15) * 4;
;     f32x4 va[16], vb[16];
;     int it = lo + gw; if (it >= NITEMS) return;
;     TrItem ta = p0_item(F, it, g4), tb = ta;
;     tr_load<NT>(va, ta, F.lane);
.LBB0_1896:
	s_abs_i32 s0, s3
	v_cvt_f32_u32_e32 v1, s0
	s_sub_i32 s1, 0, s0
	v_rcp_iflag_f32_e32 v1, v1
	s_nop 0
	v_mul_f32_e32 v1, 0x4f7ffffe, v1
	v_cvt_u32_f32_e32 v1, v1
	s_nop 0
	v_readfirstlane_b32 s2, v1
	s_mul_i32 s1, s1, s2
	s_mul_hi_u32 s1, s2, s1
	s_add_i32 s2, s2, s1
	s_mul_hi_u32 s1, s2, 0xac0
	s_mul_i32 s1, s1, s0
	s_sub_i32 s1, 0xac0, s1
	s_sub_i32 s2, s1, s0
	s_cmp_ge_u32 s1, s0
	s_cselect_b32 s1, s2, s1
	s_sub_i32 s2, s1, s0
	s_cmp_ge_u32 s1, s0
	s_cselect_b32 s12, s2, s1
	s_cmp_lt_i32 s95, s12
	s_cbranch_scc1 .LBB0_2093
	v_mov_b32_e32 v4, v0
	s_nop 0
	v_readfirstlane_b32 s0, v4
	s_ashr_i32 s13, s0, 6
	s_sub_i32 s0, s95, s12
	s_lshl_b32 s0, s0, 3
	s_add_i32 s0, s0, s13
	s_add_i32 s20, s0, 0x9e40
	s_cmp_gt_i32 s20, 0xc93f
	s_cbranch_scc1 .LBB0_2093
	s_add_u32 s2, s82, 0x2000000
	s_addc_u32 s16, s83, 0
	s_add_u32 s17, s82, 0x9800000
	s_addc_u32 s18, s83, 0
	s_add_u32 s0, s82, 0x17000000
	v_lshlrev_b32_e32 v1, 2, v4
	s_addc_u32 s1, s83, 0
	s_cmpk_gt_i32 s20, 0x383f
	v_and_b32_e32 v134, 60, v1
	s_cbranch_scc0 .LBB0_1902
	s_cmpk_gt_u32 s20, 0x483f
	s_cbranch_scc0 .LBB0_1903
	s_cmpk_gt_u32 s20, 0x9e3f
	s_cbranch_scc0 .LBB0_1904
	s_add_i32 s4, s20, 0x61c0
	s_and_b32 s5, s4, 0xffff
	s_mul_i32 s5, s5, 0xbe83
	s_lshr_b32 s6, s5, 23
	s_mul_i32 s5, s6, 0xac
	s_sub_i32 s4, s4, s5
	s_lshl_b32 s4, s4, 6
	s_and_b32 s7, s4, 0xffc0
	s_lshl_b32 s4, s7, 14
	s_add_u32 s4, s78, s4
	s_addc_u32 s5, s79, 0
	s_lshl_b32 s8, s6, 8
	s_add_u32 s4, s4, s8
	s_addc_u32 s5, s5, 0
	v_lshlrev_b32_e32 v2, 2, v134
	s_waitcnt lgkmcnt(0)
	v_mov_b32_e32 v3, 0
	s_mul_i32 s6, s6, 0x158000
	v_lshl_add_u64 v[2:3], s[4:5], 0, v[2:3]
	s_add_u32 s4, s0, s6
	s_addc_u32 s5, s1, 0
	s_lshl_b32 s6, s7, 1
	s_add_u32 s6, s4, s6
	s_addc_u32 s7, s5, 0
	s_mov_b64 s[4:5], 0
	s_branch .LBB0_1905
